# S5 pass 2 recurrence: bu rows read up front, state update with scalar f32 mul/fma/add instead of packed f32 ops (same operations per component)
# speedup vs baseline: 1.0066x; 1.0066x over previous
; DI u16 f2bf(float x) { return (u16)(pk2(x, 0.f) & 0xffffu); }
; template <bool OUT>
; DI void s5_item(int wv0, PP p, int item, unsigned char* smem) {
;     ...
; #pragma unroll 4
;     for (int t = 0; t < 16; ++t) {
;       const float bur = sBU[t * 132 + lane], bui = sBU[t * 132 + 64 + lane];
;       const float nr = lbr * hr - lbi * hi + bur;
;       const float nim = lbr * hi + lbi * hr + bui;
;       hr = nr;
;       hi = nim;
;       if (OUT) {
;         sH[t * 136 + lane] = f2bf(hr);
;         sH[t * 136 + 64 + lane] = f2bf(hi);
;       }
;     }
.LBB0_784:
	v_add_u32_e32 v117, 32, v62
	v_add_u32_e32 v118, 1088, v62
	v_add_u32_e32 v119, 2144, v62
	v_add_u32_e32 v120, 3200, v62
	v_add_u32_e32 v121, 4256, v62
	v_add_u32_e32 v122, 5312, v62
	v_add_u32_e32 v123, 6368, v62
	v_add_u32_e32 v124, 7424, v62
	ds_read2st64_b32 v[152:153], v117 offset1:1
	ds_read2_b32 v[154:155], v117 offset0:132 offset1:196
	ds_read2st64_b32 v[156:157], v118 offset1:1
	ds_read2_b32 v[158:159], v118 offset0:132 offset1:196
	ds_read2st64_b32 v[160:161], v119 offset1:1
	ds_read2_b32 v[162:163], v119 offset0:132 offset1:196
	ds_read2st64_b32 v[164:165], v120 offset1:1
	ds_read2_b32 v[166:167], v120 offset0:132 offset1:196
	ds_read2st64_b32 v[168:169], v121 offset1:1
	ds_read2_b32 v[170:171], v121 offset0:132 offset1:196
	ds_read2st64_b32 v[172:173], v122 offset1:1
	ds_read2_b32 v[174:175], v122 offset0:132 offset1:196
	ds_read2st64_b32 v[176:177], v123 offset1:1
	ds_read2_b32 v[178:179], v123 offset0:132 offset1:196
	ds_read2st64_b32 v[180:181], v124 offset1:1
	ds_read2_b32 v[182:183], v124 offset0:132 offset1:196
	v_add_u32_e32 v126, 0x12820, v63
	s_waitcnt lgkmcnt(0)
	v_mul_f32_e32 v184, v70, v69
	v_mul_f32_e32 v185, v71, v69
	v_fma_f32 v186, v66, v68, -v184
	v_fma_f32 v187, v67, v68, v185
	v_add_f32_e32 v192, v186, v152
	v_add_f32_e32 v193, v187, v153
	v_cvt_pk_bf16_f32 v190, v192, s0
	ds_write_b16 v126, v190
	v_cvt_pk_bf16_f32 v191, v193, s0
	ds_write_b16 v126, v191 offset:128
	v_mul_f32_e32 v184, v70, v193
	v_mul_f32_e32 v185, v71, v193
	v_fma_f32 v186, v66, v192, -v184
	v_fma_f32 v187, v67, v192, v185
	v_add_f32_e32 v68, v186, v154
	v_add_f32_e32 v69, v187, v155
	v_cvt_pk_bf16_f32 v190, v68, s0
	ds_write_b16 v126, v190 offset:272
	v_cvt_pk_bf16_f32 v191, v69, s0
	ds_write_b16 v126, v191 offset:400
	v_mul_f32_e32 v184, v70, v69
	v_mul_f32_e32 v185, v71, v69
	v_fma_f32 v186, v66, v68, -v184
	v_fma_f32 v187, v67, v68, v185
	v_add_f32_e32 v192, v186, v156
	v_add_f32_e32 v193, v187, v157
	v_cvt_pk_bf16_f32 v190, v192, s0
	ds_write_b16 v126, v190 offset:544
	v_cvt_pk_bf16_f32 v191, v193, s0
	ds_write_b16 v126, v191 offset:672
	v_mul_f32_e32 v184, v70, v193
	v_mul_f32_e32 v185, v71, v193
	v_fma_f32 v186, v66, v192, -v184
	v_fma_f32 v187, v67, v192, v185
	v_add_f32_e32 v68, v186, v158
	v_add_f32_e32 v69, v187, v159
	v_cvt_pk_bf16_f32 v190, v68, s0
	ds_write_b16 v126, v190 offset:816
	v_cvt_pk_bf16_f32 v191, v69, s0
	ds_write_b16 v126, v191 offset:944
	v_mul_f32_e32 v184, v70, v69
	v_mul_f32_e32 v185, v71, v69
	v_fma_f32 v186, v66, v68, -v184
	v_fma_f32 v187, v67, v68, v185
	v_add_f32_e32 v192, v186, v160
	v_add_f32_e32 v193, v187, v161
	v_cvt_pk_bf16_f32 v190, v192, s0
	ds_write_b16 v126, v190 offset:1088
	v_cvt_pk_bf16_f32 v191, v193, s0
	ds_write_b16 v126, v191 offset:1216
	v_mul_f32_e32 v184, v70, v193
	v_mul_f32_e32 v185, v71, v193
	v_fma_f32 v186, v66, v192, -v184
	v_fma_f32 v187, v67, v192, v185
	v_add_f32_e32 v68, v186, v162
	v_add_f32_e32 v69, v187, v163
	v_cvt_pk_bf16_f32 v190, v68, s0
	ds_write_b16 v126, v190 offset:1360
	v_cvt_pk_bf16_f32 v191, v69, s0
	ds_write_b16 v126, v191 offset:1488
	v_mul_f32_e32 v184, v70, v69
	v_mul_f32_e32 v185, v71, v69
	v_fma_f32 v186, v66, v68, -v184
	v_fma_f32 v187, v67, v68, v185
	v_add_f32_e32 v192, v186, v164
	v_add_f32_e32 v193, v187, v165
	v_cvt_pk_bf16_f32 v190, v192, s0
	ds_write_b16 v126, v190 offset:1632
	v_cvt_pk_bf16_f32 v191, v193, s0
	ds_write_b16 v126, v191 offset:1760
	v_mul_f32_e32 v184, v70, v193
	v_mul_f32_e32 v185, v71, v193
	v_fma_f32 v186, v66, v192, -v184
	v_fma_f32 v187, v67, v192, v185
	v_add_f32_e32 v68, v186, v166
	v_add_f32_e32 v69, v187, v167
	v_cvt_pk_bf16_f32 v190, v68, s0
	ds_write_b16 v126, v190 offset:1904
	v_cvt_pk_bf16_f32 v191, v69, s0
	ds_write_b16 v126, v191 offset:2032
	v_mul_f32_e32 v184, v70, v69
	v_mul_f32_e32 v185, v71, v69
	v_fma_f32 v186, v66, v68, -v184
	v_fma_f32 v187, v67, v68, v185
	v_add_f32_e32 v192, v186, v168
	v_add_f32_e32 v193, v187, v169
	v_cvt_pk_bf16_f32 v190, v192, s0
	ds_write_b16 v126, v190 offset:2176
	v_cvt_pk_bf16_f32 v191, v193, s0
	ds_write_b16 v126, v191 offset:2304
	v_mul_f32_e32 v184, v70, v193
	v_mul_f32_e32 v185, v71, v193
	v_fma_f32 v186, v66, v192, -v184
	v_fma_f32 v187, v67, v192, v185
	v_add_f32_e32 v68, v186, v170
	v_add_f32_e32 v69, v187, v171
	v_cvt_pk_bf16_f32 v190, v68, s0
	ds_write_b16 v126, v190 offset:2448
	v_cvt_pk_bf16_f32 v191, v69, s0
	ds_write_b16 v126, v191 offset:2576
	v_mul_f32_e32 v184, v70, v69
	v_mul_f32_e32 v185, v71, v69
	v_fma_f32 v186, v66, v68, -v184
	v_fma_f32 v187, v67, v68, v185
	v_add_f32_e32 v192, v186, v172
	v_add_f32_e32 v193, v187, v173
	v_cvt_pk_bf16_f32 v190, v192, s0
	ds_write_b16 v126, v190 offset:2720
	v_cvt_pk_bf16_f32 v191, v193, s0
	ds_write_b16 v126, v191 offset:2848
	v_mul_f32_e32 v184, v70, v193
	v_mul_f32_e32 v185, v71, v193
	v_fma_f32 v186, v66, v192, -v184
	v_fma_f32 v187, v67, v192, v185
	v_add_f32_e32 v68, v186, v174
	v_add_f32_e32 v69, v187, v175
	v_cvt_pk_bf16_f32 v190, v68, s0
	ds_write_b16 v126, v190 offset:2992
	v_cvt_pk_bf16_f32 v191, v69, s0
	ds_write_b16 v126, v191 offset:3120
	v_mul_f32_e32 v184, v70, v69
	v_mul_f32_e32 v185, v71, v69
	v_fma_f32 v186, v66, v68, -v184
	v_fma_f32 v187, v67, v68, v185
	v_add_f32_e32 v192, v186, v176
	v_add_f32_e32 v193, v187, v177
	v_cvt_pk_bf16_f32 v190, v192, s0
	ds_write_b16 v126, v190 offset:3264
	v_cvt_pk_bf16_f32 v191, v193, s0
	ds_write_b16 v126, v191 offset:3392
	v_mul_f32_e32 v184, v70, v193
	v_mul_f32_e32 v185, v71, v193
	v_fma_f32 v186, v66, v192, -v184
	v_fma_f32 v187, v67, v192, v185
	v_add_f32_e32 v68, v186, v178
	v_add_f32_e32 v69, v187, v179
	v_cvt_pk_bf16_f32 v190, v68, s0
	ds_write_b16 v126, v190 offset:3536
	v_cvt_pk_bf16_f32 v191, v69, s0
	ds_write_b16 v126, v191 offset:3664
	v_mul_f32_e32 v184, v70, v69
	v_mul_f32_e32 v185, v71, v69
	v_fma_f32 v186, v66, v68, -v184
	v_fma_f32 v187, v67, v68, v185
	v_add_f32_e32 v192, v186, v180
	v_add_f32_e32 v193, v187, v181
	v_cvt_pk_bf16_f32 v190, v192, s0
	ds_write_b16 v126, v190 offset:3808
	v_cvt_pk_bf16_f32 v191, v193, s0
	ds_write_b16 v126, v191 offset:3936
	v_mul_f32_e32 v184, v70, v193
	v_mul_f32_e32 v185, v71, v193
	v_fma_f32 v186, v66, v192, -v184
	v_fma_f32 v187, v67, v192, v185
	v_add_f32_e32 v68, v186, v182
	v_add_f32_e32 v69, v187, v183
	v_cvt_pk_bf16_f32 v190, v68, s0
	ds_write_b16 v126, v190 offset:4080
	v_cvt_pk_bf16_f32 v191, v69, s0
	ds_write_b16 v126, v191 offset:4208
	s_lshl_b64 s[2:3], s[2:3], 1
	v_readlane_b32 s4, v247, 42
	s_add_u32 s2, s4, s2
	v_readlane_b32 s4, v247, 43
	s_addc_u32 s3, s4, s3
	v_readlane_b32 s4, v247, 46
	s_waitcnt lgkmcnt(0)
	s_barrier
; DI u16 f2bf(float x) { return (u16)(pk2(x, 0.f) & 0xffffu); }
; DI float bf2f(u16 h) { return __uint_as_float(((unsigned)h) << 16); }
; DI f32x4 mfma16(bf16x8 a, bf16x8 b, f32x4 c) { return __builtin_amdgcn_mfma_f32_16x16x32_bf16(a, b, c, 0, 0, 0); }
; template <bool OUT>
; DI void s5_item(int wv0, PP p, int item, unsigned char* smem) {
;     ...
;   for (int sub = 0; sub < 4; ++sub) {
;     const bf16x8 ua = uall[sub];
; #pragma unroll
;     for (int nt = 0; nt < 8; ++nt) {
;       const f32x4 a = mfma16(ua, bb[nt], f32x4{0.f, 0.f, 0.f, 0.f});
; #pragma unroll
;       for (int j = 0; j < 4; ++j) sBU[(4 * fq + j) * 132 + 16 * nt + fr] = a[j];
;     }
;     __syncthreads();
;     ...
;     if (OUT) {
;       f32x4 y = {0.f, 0.f, 0.f, 0.f};
; #pragma unroll
;       for (int ks = 0; ks < 4; ++ks) y = mfma16(*(const bf16x8*)(sH + fr * 136 + 32 * ks + 8 * fq), cf[ks], y);
; #pragma unroll
;       for (int j = 0; j < 4; ++j) {
;         const size_t o = (size_t)(sub * 16 + 4 * fq + j) * 512 + fr;
;         YS[o] = f2bf(gelu_t(y[j] + dk * bf2f(usk[sub][j])));
;       }
;       __syncthreads();
	v_add_u32_e32 v62, s4, v110
	v_add_u32_e32 v0, v62, v0
	ds_read_b128 v[62:65], v0
	ds_read_b128 v[110:113], v0 offset:64
	s_waitcnt vmcnt(15)
	v_lshlrev_b32_e32 v109, 16, v109
	s_waitcnt lgkmcnt(1)
	v_mfma_f32_16x16x32_bf16 v[62:65], v[62:65], v[14:17], 0
	s_lshl_b32 s4, s8, 1
	s_add_u32 s2, s2, s4
	s_addc_u32 s3, s3, 0
	s_waitcnt lgkmcnt(0)
	v_mfma_f32_16x16x32_bf16 v[62:65], v[110:113], v[10:13], v[62:65]
	ds_read_b128 v[110:113], v0 offset:128
	s_waitcnt lgkmcnt(0)
	v_mfma_f32_16x16x32_bf16 v[62:65], v[110:113], v[6:9], v[62:65]
	ds_read_b128 v[110:113], v0 offset:192
	s_waitcnt lgkmcnt(0)
	v_mfma_f32_16x16x32_bf16 v[62:65], v[110:113], v[2:5], v[62:65]
	s_nop 7
	v_fma_f32 v62, v72, v109, v62
	v_mul_f32_e32 v109, 0x3d372713, v62
	v_mul_f32_e32 v109, v62, v109
	v_fma_f32 v109, v62, v109, v62
	v_mul_f32_e32 v109, 0x3f4c422a, v109
	v_add_f32_e32 v109, v109, v109
	v_mul_f32_e32 v109, 0x3fb8aa3b, v109
	v_exp_f32_e32 v109, v109
	v_mul_f32_e32 v62, 0.5, v62
	v_add_f32_e32 v109, 1.0, v109
	v_div_scale_f32 v110, s[4:5], v109, v109, 2.0
	v_rcp_f32_e32 v111, v110
	s_nop 0
	v_fma_f32 v112, -v110, v111, 1.0
	v_fmac_f32_e32 v111, v112, v111
	v_div_scale_f32 v112, vcc, 2.0, v109, 2.0
	v_mul_f32_e32 v113, v112, v111
	v_fma_f32 v114, -v110, v113, v112
	v_fmac_f32_e32 v113, v114, v111
	v_fma_f32 v110, -v110, v113, v112
	v_div_fmas_f32 v110, v110, v111, v113
	v_div_fixup_f32 v109, v110, v109, 2.0
	v_sub_f32_e32 v109, 1.0, v109
	v_add_f32_e32 v109, 1.0, v109
	v_mul_f32_e32 v62, v62, v109
	v_cvt_pk_bf16_f32 v62, v62, s0
	global_store_short v108, v62, s[2:3]
	s_waitcnt vmcnt(15)
	v_lshlrev_b32_e32 v62, 16, v104
	v_fma_f32 v62, v72, v62, v63
	v_mul_f32_e32 v63, 0x3d372713, v62
	v_mul_f32_e32 v63, v62, v63
	v_fma_f32 v63, v62, v63, v62
	v_mul_f32_e32 v63, 0x3f4c422a, v63
	v_add_f32_e32 v63, v63, v63
	v_mul_f32_e32 v63, 0x3fb8aa3b, v63
	v_exp_f32_e32 v63, v63
	v_mul_f32_e32 v62, 0.5, v62
	v_add_f32_e32 v63, 1.0, v63
	v_div_scale_f32 v104, s[4:5], v63, v63, 2.0
	v_rcp_f32_e32 v108, v104
	s_nop 0
	v_fma_f32 v109, -v104, v108, 1.0
	v_fmac_f32_e32 v108, v109, v108
	v_div_scale_f32 v109, vcc, 2.0, v63, 2.0
	v_mul_f32_e32 v110, v109, v108
	v_fma_f32 v111, -v104, v110, v109
	v_fmac_f32_e32 v110, v111, v108
	v_fma_f32 v104, -v104, v110, v109
	v_div_fmas_f32 v104, v104, v108, v110
	v_div_fixup_f32 v63, v104, v63, 2.0
	v_sub_f32_e32 v63, 1.0, v63
	v_add_f32_e32 v63, 1.0, v63
	v_mul_f32_e32 v62, v62, v63
	v_cvt_pk_bf16_f32 v62, v62, s0
	global_store_short v103, v62, s[2:3]
	s_waitcnt vmcnt(15)
	v_lshlrev_b32_e32 v62, 16, v102
	v_fma_f32 v62, v72, v62, v64
	v_mul_f32_e32 v63, 0x3d372713, v62
	v_mul_f32_e32 v63, v62, v63
	v_fma_f32 v63, v62, v63, v62
	v_mul_f32_e32 v63, 0x3f4c422a, v63
	v_add_f32_e32 v63, v63, v63
	v_mul_f32_e32 v63, 0x3fb8aa3b, v63
	v_exp_f32_e32 v63, v63
	v_mul_f32_e32 v62, 0.5, v62
	v_add_f32_e32 v63, 1.0, v63
	v_div_scale_f32 v64, s[4:5], v63, v63, 2.0
	v_rcp_f32_e32 v102, v64
	s_nop 0
	v_fma_f32 v103, -v64, v102, 1.0
	v_fmac_f32_e32 v102, v103, v102
	v_div_scale_f32 v103, vcc, 2.0, v63, 2.0
	v_mul_f32_e32 v104, v103, v102
	v_fma_f32 v108, -v64, v104, v103
	v_fmac_f32_e32 v104, v108, v102
	v_fma_f32 v64, -v64, v104, v103
	v_div_fmas_f32 v64, v64, v102, v104
	v_div_fixup_f32 v63, v64, v63, 2.0
	v_sub_f32_e32 v63, 1.0, v63
	v_add_f32_e32 v63, 1.0, v63
	v_mul_f32_e32 v62, v62, v63
	v_cvt_pk_bf16_f32 v62, v62, s0
	global_store_short v101, v62, s[2:3]
	s_waitcnt vmcnt(15)
	v_lshlrev_b32_e32 v62, 16, v100
	v_fmac_f32_e32 v65, v72, v62
	v_mul_f32_e32 v62, 0x3d372713, v65
	v_mul_f32_e32 v62, v65, v62
	v_fma_f32 v62, v65, v62, v65
	v_mul_f32_e32 v62, 0x3f4c422a, v62
	v_add_f32_e32 v62, v62, v62
	v_mul_f32_e32 v62, 0x3fb8aa3b, v62
	v_exp_f32_e32 v62, v62
	s_nop 0
	v_add_f32_e32 v62, 1.0, v62
	v_div_scale_f32 v63, s[4:5], v62, v62, 2.0
	v_rcp_f32_e32 v64, v63
	s_mov_b32 s4, 16
	v_fma_f32 v100, -v63, v64, 1.0
	v_fmac_f32_e32 v64, v100, v64
	v_div_scale_f32 v100, vcc, 2.0, v62, 2.0
	v_mul_f32_e32 v101, v100, v64
	v_fma_f32 v102, -v63, v101, v100
	v_fmac_f32_e32 v101, v102, v64
	v_fma_f32 v63, -v63, v101, v100
	v_div_fmas_f32 v63, v63, v64, v101
	v_div_fixup_f32 v62, v63, v62, 2.0
	v_sub_f32_e32 v62, 1.0, v62
	v_mul_f32_e32 v63, 0.5, v65
	v_add_f32_e32 v62, 1.0, v62
	v_mfma_f32_16x16x32_bf16 v[100:103], v[58:61], v[26:29], 0
	v_mul_f32_e32 v62, v63, v62
	v_cvt_pk_bf16_f32 v62, v62, s0
	global_store_short v99, v62, s[2:3]
	v_add_u32_e32 v63, v105, v106
	v_add_u32_e32 v62, v105, v107
	s_barrier
	s_nop 1
	ds_write_b32 v63, v100 offset:8192
	ds_write_b32 v62, v101 offset:8192
	ds_write_b32 v62, v102 offset:8720
	ds_write_b32 v62, v103 offset:9248
	v_mfma_f32_16x16x32_bf16 v[100:103], v[58:61], v[22:25], 0
	s_nop 7
	ds_write_b32 v63, v100 offset:8256
	ds_write_b32 v62, v101 offset:8256
	ds_write_b32 v62, v102 offset:8784
	ds_write_b32 v62, v103 offset:9312
	v_mfma_f32_16x16x32_bf16 v[100:103], v[58:61], v[34:37], 0
	s_nop 7
	ds_write_b32 v63, v100 offset:8320
	ds_write_b32 v62, v101 offset:8320
	ds_write_b32 v62, v102 offset:8848
	ds_write_b32 v62, v103 offset:9376
	v_mfma_f32_16x16x32_bf16 v[100:103], v[58:61], v[30:33], 0
	s_nop 7
	ds_write_b32 v63, v100 offset:8384
	ds_write_b32 v62, v101 offset:8384
	ds_write_b32 v62, v102 offset:8912
	ds_write_b32 v62, v103 offset:9440
	v_mfma_f32_16x16x32_bf16 v[100:103], v[58:61], v[42:45], 0
	s_nop 7
	ds_write_b32 v63, v100 offset:8448
	ds_write_b32 v62, v101 offset:8448
	ds_write_b32 v62, v102 offset:8976
	ds_write_b32 v62, v103 offset:9504
	v_mfma_f32_16x16x32_bf16 v[100:103], v[58:61], v[38:41], 0
	s_nop 7
	ds_write_b32 v63, v100 offset:8512
	ds_write_b32 v62, v101 offset:8512
	ds_write_b32 v62, v102 offset:9040
	ds_write_b32 v62, v103 offset:9568
	v_mfma_f32_16x16x32_bf16 v[100:103], v[58:61], v[50:53], 0
	s_nop 7
	ds_write_b32 v63, v100 offset:8576
	ds_write_b32 v62, v101 offset:8576
	ds_write_b32 v62, v102 offset:9104
	ds_write_b32 v62, v103 offset:9632
	v_mfma_f32_16x16x32_bf16 v[58:61], v[58:61], v[46:49], 0
	s_nop 7
	ds_write_b32 v63, v58 offset:8640
	ds_write_b32 v62, v59 offset:8640
	ds_write_b32 v62, v60 offset:9168
	ds_write_b32 v62, v61 offset:9696
	v_mov_b32_e32 v58, v82
	v_mov_b32_e32 v59, v81
	s_waitcnt lgkmcnt(0)
	s_barrier
; DI u16 f2bf(float x) { return (u16)(pk2(x, 0.f) & 0xffffu); }
; template <bool OUT>
; DI void s5_item(int wv0, PP p, int item, unsigned char* smem) {
;     ...
; #pragma unroll 4
;     for (int t = 0; t < 16; ++t) {
;       const float bur = sBU[t * 132 + lane], bui = sBU[t * 132 + 64 + lane];
;       const float nr = lbr * hr - lbi * hi + bur;
;       const float nim = lbr * hi + lbi * hr + bui;
;       hr = nr;
;       hi = nim;
;       if (OUT) {
;         sH[t * 136 + lane] = f2bf(hr);
;         sH[t * 136 + 64 + lane] = f2bf(hi);
;       }
;     }
.LBB0_786:
	v_add_u32_e32 v117, 32, v58
	v_add_u32_e32 v118, 1088, v58
	v_add_u32_e32 v119, 2144, v58
	v_add_u32_e32 v120, 3200, v58
	v_add_u32_e32 v121, 4256, v58
	v_add_u32_e32 v122, 5312, v58
	v_add_u32_e32 v123, 6368, v58
	v_add_u32_e32 v124, 7424, v58
	ds_read2st64_b32 v[152:153], v117 offset1:1
	ds_read2_b32 v[154:155], v117 offset0:132 offset1:196
	ds_read2st64_b32 v[156:157], v118 offset1:1
	ds_read2_b32 v[158:159], v118 offset0:132 offset1:196
	ds_read2st64_b32 v[160:161], v119 offset1:1
	ds_read2_b32 v[162:163], v119 offset0:132 offset1:196
	ds_read2st64_b32 v[164:165], v120 offset1:1
	ds_read2_b32 v[166:167], v120 offset0:132 offset1:196
	ds_read2st64_b32 v[168:169], v121 offset1:1
	ds_read2_b32 v[170:171], v121 offset0:132 offset1:196
	ds_read2st64_b32 v[172:173], v122 offset1:1
	ds_read2_b32 v[174:175], v122 offset0:132 offset1:196
	ds_read2st64_b32 v[176:177], v123 offset1:1
	ds_read2_b32 v[178:179], v123 offset0:132 offset1:196
	ds_read2st64_b32 v[180:181], v124 offset1:1
	ds_read2_b32 v[182:183], v124 offset0:132 offset1:196
	v_add_u32_e32 v126, 0x12820, v59
	s_waitcnt lgkmcnt(0)
	v_mul_f32_e32 v184, v70, v69
	v_mul_f32_e32 v185, v71, v69
	v_fma_f32 v186, v66, v68, -v184
	v_fma_f32 v187, v67, v68, v185
	v_add_f32_e32 v192, v186, v152
	v_add_f32_e32 v193, v187, v153
	v_cvt_pk_bf16_f32 v190, v192, s0
	ds_write_b16 v126, v190
	v_cvt_pk_bf16_f32 v191, v193, s0
	ds_write_b16 v126, v191 offset:128
	v_mul_f32_e32 v184, v70, v193
	v_mul_f32_e32 v185, v71, v193
	v_fma_f32 v186, v66, v192, -v184
	v_fma_f32 v187, v67, v192, v185
	v_add_f32_e32 v68, v186, v154
	v_add_f32_e32 v69, v187, v155
	v_cvt_pk_bf16_f32 v190, v68, s0
	ds_write_b16 v126, v190 offset:272
	v_cvt_pk_bf16_f32 v191, v69, s0
	ds_write_b16 v126, v191 offset:400
	v_mul_f32_e32 v184, v70, v69
	v_mul_f32_e32 v185, v71, v69
	v_fma_f32 v186, v66, v68, -v184
	v_fma_f32 v187, v67, v68, v185
	v_add_f32_e32 v192, v186, v156
	v_add_f32_e32 v193, v187, v157
	v_cvt_pk_bf16_f32 v190, v192, s0
	ds_write_b16 v126, v190 offset:544
	v_cvt_pk_bf16_f32 v191, v193, s0
	ds_write_b16 v126, v191 offset:672
	v_mul_f32_e32 v184, v70, v193
	v_mul_f32_e32 v185, v71, v193
	v_fma_f32 v186, v66, v192, -v184
	v_fma_f32 v187, v67, v192, v185
	v_add_f32_e32 v68, v186, v158
	v_add_f32_e32 v69, v187, v159
	v_cvt_pk_bf16_f32 v190, v68, s0
	ds_write_b16 v126, v190 offset:816
	v_cvt_pk_bf16_f32 v191, v69, s0
	ds_write_b16 v126, v191 offset:944
	v_mul_f32_e32 v184, v70, v69
	v_mul_f32_e32 v185, v71, v69
	v_fma_f32 v186, v66, v68, -v184
	v_fma_f32 v187, v67, v68, v185
	v_add_f32_e32 v192, v186, v160
	v_add_f32_e32 v193, v187, v161
	v_cvt_pk_bf16_f32 v190, v192, s0
	ds_write_b16 v126, v190 offset:1088
	v_cvt_pk_bf16_f32 v191, v193, s0
	ds_write_b16 v126, v191 offset:1216
	v_mul_f32_e32 v184, v70, v193
	v_mul_f32_e32 v185, v71, v193
	v_fma_f32 v186, v66, v192, -v184
	v_fma_f32 v187, v67, v192, v185
	v_add_f32_e32 v68, v186, v162
	v_add_f32_e32 v69, v187, v163
	v_cvt_pk_bf16_f32 v190, v68, s0
	ds_write_b16 v126, v190 offset:1360
	v_cvt_pk_bf16_f32 v191, v69, s0
	ds_write_b16 v126, v191 offset:1488
	v_mul_f32_e32 v184, v70, v69
	v_mul_f32_e32 v185, v71, v69
	v_fma_f32 v186, v66, v68, -v184
	v_fma_f32 v187, v67, v68, v185
	v_add_f32_e32 v192, v186, v164
	v_add_f32_e32 v193, v187, v165
	v_cvt_pk_bf16_f32 v190, v192, s0
	ds_write_b16 v126, v190 offset:1632
	v_cvt_pk_bf16_f32 v191, v193, s0
	ds_write_b16 v126, v191 offset:1760
	v_mul_f32_e32 v184, v70, v193
	v_mul_f32_e32 v185, v71, v193
	v_fma_f32 v186, v66, v192, -v184
	v_fma_f32 v187, v67, v192, v185
	v_add_f32_e32 v68, v186, v166
	v_add_f32_e32 v69, v187, v167
	v_cvt_pk_bf16_f32 v190, v68, s0
	ds_write_b16 v126, v190 offset:1904
	v_cvt_pk_bf16_f32 v191, v69, s0
	ds_write_b16 v126, v191 offset:2032
	v_mul_f32_e32 v184, v70, v69
	v_mul_f32_e32 v185, v71, v69
	v_fma_f32 v186, v66, v68, -v184
	v_fma_f32 v187, v67, v68, v185
	v_add_f32_e32 v192, v186, v168
	v_add_f32_e32 v193, v187, v169
	v_cvt_pk_bf16_f32 v190, v192, s0
	ds_write_b16 v126, v190 offset:2176
	v_cvt_pk_bf16_f32 v191, v193, s0
	ds_write_b16 v126, v191 offset:2304
	v_mul_f32_e32 v184, v70, v193
	v_mul_f32_e32 v185, v71, v193
	v_fma_f32 v186, v66, v192, -v184
	v_fma_f32 v187, v67, v192, v185
	v_add_f32_e32 v68, v186, v170
	v_add_f32_e32 v69, v187, v171
	v_cvt_pk_bf16_f32 v190, v68, s0
	ds_write_b16 v126, v190 offset:2448
	v_cvt_pk_bf16_f32 v191, v69, s0
	ds_write_b16 v126, v191 offset:2576
	v_mul_f32_e32 v184, v70, v69
	v_mul_f32_e32 v185, v71, v69
	v_fma_f32 v186, v66, v68, -v184
	v_fma_f32 v187, v67, v68, v185
	v_add_f32_e32 v192, v186, v172
	v_add_f32_e32 v193, v187, v173
	v_cvt_pk_bf16_f32 v190, v192, s0
	ds_write_b16 v126, v190 offset:2720
	v_cvt_pk_bf16_f32 v191, v193, s0
	ds_write_b16 v126, v191 offset:2848
	v_mul_f32_e32 v184, v70, v193
	v_mul_f32_e32 v185, v71, v193
	v_fma_f32 v186, v66, v192, -v184
	v_fma_f32 v187, v67, v192, v185
	v_add_f32_e32 v68, v186, v174
	v_add_f32_e32 v69, v187, v175
	v_cvt_pk_bf16_f32 v190, v68, s0
	ds_write_b16 v126, v190 offset:2992
	v_cvt_pk_bf16_f32 v191, v69, s0
	ds_write_b16 v126, v191 offset:3120
	v_mul_f32_e32 v184, v70, v69
	v_mul_f32_e32 v185, v71, v69
	v_fma_f32 v186, v66, v68, -v184
	v_fma_f32 v187, v67, v68, v185
	v_add_f32_e32 v192, v186, v176
	v_add_f32_e32 v193, v187, v177
	v_cvt_pk_bf16_f32 v190, v192, s0
	ds_write_b16 v126, v190 offset:3264
	v_cvt_pk_bf16_f32 v191, v193, s0
	ds_write_b16 v126, v191 offset:3392
	v_mul_f32_e32 v184, v70, v193
	v_mul_f32_e32 v185, v71, v193
	v_fma_f32 v186, v66, v192, -v184
	v_fma_f32 v187, v67, v192, v185
	v_add_f32_e32 v68, v186, v178
	v_add_f32_e32 v69, v187, v179
	v_cvt_pk_bf16_f32 v190, v68, s0
	ds_write_b16 v126, v190 offset:3536
	v_cvt_pk_bf16_f32 v191, v69, s0
	ds_write_b16 v126, v191 offset:3664
	v_mul_f32_e32 v184, v70, v69
	v_mul_f32_e32 v185, v71, v69
	v_fma_f32 v186, v66, v68, -v184
	v_fma_f32 v187, v67, v68, v185
	v_add_f32_e32 v192, v186, v180
	v_add_f32_e32 v193, v187, v181
	v_cvt_pk_bf16_f32 v190, v192, s0
	ds_write_b16 v126, v190 offset:3808
	v_cvt_pk_bf16_f32 v191, v193, s0
	ds_write_b16 v126, v191 offset:3936
	v_mul_f32_e32 v184, v70, v193
	v_mul_f32_e32 v185, v71, v193
	v_fma_f32 v186, v66, v192, -v184
	v_fma_f32 v187, v67, v192, v185
	v_add_f32_e32 v68, v186, v182
	v_add_f32_e32 v69, v187, v183
	v_cvt_pk_bf16_f32 v190, v68, s0
	ds_write_b16 v126, v190 offset:4080
	v_cvt_pk_bf16_f32 v191, v69, s0
	ds_write_b16 v126, v191 offset:4208
	s_waitcnt lgkmcnt(0)
	s_barrier
; DI u16 f2bf(float x) { return (u16)(pk2(x, 0.f) & 0xffffu); }
; DI float bf2f(u16 h) { return __uint_as_float(((unsigned)h) << 16); }
; DI f32x4 mfma16(bf16x8 a, bf16x8 b, f32x4 c) { return __builtin_amdgcn_mfma_f32_16x16x32_bf16(a, b, c, 0, 0, 0); }
; template <bool OUT>
; DI void s5_item(int wv0, PP p, int item, unsigned char* smem) {
;     ...
;   for (int sub = 0; sub < 4; ++sub) {
;     const bf16x8 ua = uall[sub];
; #pragma unroll
;     for (int nt = 0; nt < 8; ++nt) {
;       const f32x4 a = mfma16(ua, bb[nt], f32x4{0.f, 0.f, 0.f, 0.f});
; #pragma unroll
;       for (int j = 0; j < 4; ++j) sBU[(4 * fq + j) * 132 + 16 * nt + fr] = a[j];
;     }
;     __syncthreads();
;     ...
;     if (OUT) {
;       f32x4 y = {0.f, 0.f, 0.f, 0.f};
; #pragma unroll
;       for (int ks = 0; ks < 4; ++ks) y = mfma16(*(const bf16x8*)(sH + fr * 136 + 32 * ks + 8 * fq), cf[ks], y);
; #pragma unroll
;       for (int j = 0; j < 4; ++j) {
;         const size_t o = (size_t)(sub * 16 + 4 * fq + j) * 512 + fr;
;         YS[o] = f2bf(gelu_t(y[j] + dk * bf2f(usk[sub][j])));
;       }
;       __syncthreads();
	ds_read_b128 v[58:61], v0
	ds_read_b128 v[100:103], v0 offset:64
	s_waitcnt vmcnt(15)
	v_lshlrev_b32_e32 v64, 16, v98
	s_waitcnt lgkmcnt(1)
	v_mfma_f32_16x16x32_bf16 v[58:61], v[58:61], v[14:17], 0
	s_waitcnt lgkmcnt(0)
	v_mfma_f32_16x16x32_bf16 v[58:61], v[100:103], v[10:13], v[58:61]
	ds_read_b128 v[100:103], v0 offset:128
	s_waitcnt lgkmcnt(0)
	v_mfma_f32_16x16x32_bf16 v[58:61], v[100:103], v[6:9], v[58:61]
	ds_read_b128 v[100:103], v0 offset:192
	s_waitcnt lgkmcnt(0)
	v_mfma_f32_16x16x32_bf16 v[58:61], v[100:103], v[2:5], v[58:61]
	s_nop 7
	v_fma_f32 v58, v72, v64, v58
	v_mul_f32_e32 v64, 0x3d372713, v58
	v_mul_f32_e32 v64, v58, v64
	v_fma_f32 v64, v58, v64, v58
	v_mul_f32_e32 v64, 0x3f4c422a, v64
	v_add_f32_e32 v64, v64, v64
	v_mul_f32_e32 v64, 0x3fb8aa3b, v64
	v_exp_f32_e32 v64, v64
	v_mul_f32_e32 v58, 0.5, v58
	v_add_f32_e32 v64, 1.0, v64
	v_div_scale_f32 v65, s[4:5], v64, v64, 2.0
	v_rcp_f32_e32 v98, v65
	s_nop 0
	v_fma_f32 v99, -v65, v98, 1.0
	v_fmac_f32_e32 v98, v99, v98
	v_div_scale_f32 v99, vcc, 2.0, v64, 2.0
	v_mul_f32_e32 v100, v99, v98
	v_fma_f32 v101, -v65, v100, v99
	v_fmac_f32_e32 v100, v101, v98
	v_fma_f32 v65, -v65, v100, v99
	v_div_fmas_f32 v65, v65, v98, v100
	v_div_fixup_f32 v64, v65, v64, 2.0
	v_sub_f32_e32 v64, 1.0, v64
	v_add_f32_e32 v64, 1.0, v64
	v_mul_f32_e32 v58, v58, v64
	v_cvt_pk_bf16_f32 v58, v58, s0
	global_store_short v97, v58, s[2:3]
	s_waitcnt vmcnt(15)
	v_lshlrev_b32_e32 v58, 16, v96
	v_fma_f32 v58, v72, v58, v59
	v_mul_f32_e32 v59, 0x3d372713, v58
	v_mul_f32_e32 v59, v58, v59
	v_fma_f32 v59, v58, v59, v58
	v_mul_f32_e32 v59, 0x3f4c422a, v59
	v_add_f32_e32 v59, v59, v59
	v_mul_f32_e32 v59, 0x3fb8aa3b, v59
	v_exp_f32_e32 v59, v59
	v_mul_f32_e32 v58, 0.5, v58
	v_add_f32_e32 v59, 1.0, v59
	v_div_scale_f32 v64, s[4:5], v59, v59, 2.0
	v_rcp_f32_e32 v65, v64
	s_nop 0
	v_fma_f32 v96, -v64, v65, 1.0
	v_fmac_f32_e32 v65, v96, v65
	v_div_scale_f32 v96, vcc, 2.0, v59, 2.0
	v_mul_f32_e32 v97, v96, v65
	v_fma_f32 v98, -v64, v97, v96
	v_fmac_f32_e32 v97, v98, v65
	v_fma_f32 v64, -v64, v97, v96
	v_div_fmas_f32 v64, v64, v65, v97
	v_div_fixup_f32 v59, v64, v59, 2.0
	v_sub_f32_e32 v59, 1.0, v59
	v_add_f32_e32 v59, 1.0, v59
	v_mul_f32_e32 v58, v58, v59
	v_cvt_pk_bf16_f32 v58, v58, s0
	global_store_short v95, v58, s[2:3]
	s_waitcnt vmcnt(15)
	v_lshlrev_b32_e32 v58, 16, v94
	v_fma_f32 v58, v72, v58, v60
	v_mul_f32_e32 v59, 0x3d372713, v58
	v_mul_f32_e32 v59, v58, v59
	v_fma_f32 v59, v58, v59, v58
	v_mul_f32_e32 v59, 0x3f4c422a, v59
	v_add_f32_e32 v59, v59, v59
	v_mul_f32_e32 v59, 0x3fb8aa3b, v59
	v_exp_f32_e32 v59, v59
	v_mul_f32_e32 v58, 0.5, v58
	v_add_f32_e32 v59, 1.0, v59
	v_div_scale_f32 v60, s[4:5], v59, v59, 2.0
	v_rcp_f32_e32 v64, v60
	s_nop 0
	v_fma_f32 v65, -v60, v64, 1.0
	v_fmac_f32_e32 v64, v65, v64
	v_div_scale_f32 v65, vcc, 2.0, v59, 2.0
	v_mul_f32_e32 v94, v65, v64
	v_fma_f32 v95, -v60, v94, v65
	v_fmac_f32_e32 v94, v95, v64
	v_fma_f32 v60, -v60, v94, v65
	v_div_fmas_f32 v60, v60, v64, v94
	v_div_fixup_f32 v59, v60, v59, 2.0
	v_sub_f32_e32 v59, 1.0, v59
	v_add_f32_e32 v59, 1.0, v59
	v_mul_f32_e32 v58, v58, v59
	v_cvt_pk_bf16_f32 v58, v58, s0
	global_store_short v93, v58, s[2:3]
	s_waitcnt vmcnt(15)
	v_lshlrev_b32_e32 v58, 16, v92
	v_fmac_f32_e32 v61, v72, v58
	v_mul_f32_e32 v58, 0x3d372713, v61
	v_mul_f32_e32 v58, v61, v58
	v_fma_f32 v58, v61, v58, v61
	v_mul_f32_e32 v58, 0x3f4c422a, v58
	v_add_f32_e32 v58, v58, v58
	v_mul_f32_e32 v58, 0x3fb8aa3b, v58
	v_exp_f32_e32 v58, v58
	s_nop 0
	v_add_f32_e32 v58, 1.0, v58
	v_div_scale_f32 v59, s[4:5], v58, v58, 2.0
	v_rcp_f32_e32 v60, v59
	s_mov_b32 s4, 16
	v_fma_f32 v64, -v59, v60, 1.0
	v_fmac_f32_e32 v60, v64, v60
	v_div_scale_f32 v64, vcc, 2.0, v58, 2.0
	v_mul_f32_e32 v65, v64, v60
	v_fma_f32 v92, -v59, v65, v64
	v_fmac_f32_e32 v65, v92, v60
	v_fma_f32 v59, -v59, v65, v64
	v_div_fmas_f32 v59, v59, v60, v65
	v_div_fixup_f32 v58, v59, v58, 2.0
	v_sub_f32_e32 v58, 1.0, v58
	v_mul_f32_e32 v59, 0.5, v61
	v_add_f32_e32 v58, 1.0, v58
	v_mul_f32_e32 v58, v59, v58
	v_cvt_pk_bf16_f32 v58, v58, s0
	global_store_short v91, v58, s[2:3]
	v_mfma_f32_16x16x32_bf16 v[58:61], v[54:57], v[26:29], 0
	s_barrier
	s_nop 6
	ds_write_b32 v63, v58 offset:8192
	ds_write_b32 v62, v59 offset:8192
	ds_write_b32 v62, v60 offset:8720
	ds_write_b32 v62, v61 offset:9248
	v_mfma_f32_16x16x32_bf16 v[58:61], v[54:57], v[22:25], 0
	s_nop 7
	ds_write_b32 v63, v58 offset:8256
	ds_write_b32 v62, v59 offset:8256
	ds_write_b32 v62, v60 offset:8784
	ds_write_b32 v62, v61 offset:9312
	v_mfma_f32_16x16x32_bf16 v[58:61], v[54:57], v[34:37], 0
	s_nop 7
	ds_write_b32 v63, v58 offset:8320
	ds_write_b32 v62, v59 offset:8320
	ds_write_b32 v62, v60 offset:8848
	ds_write_b32 v62, v61 offset:9376
	v_mfma_f32_16x16x32_bf16 v[58:61], v[54:57], v[30:33], 0
	s_nop 7
	ds_write_b32 v63, v58 offset:8384
	ds_write_b32 v62, v59 offset:8384
	ds_write_b32 v62, v60 offset:8912
	ds_write_b32 v62, v61 offset:9440
	v_mfma_f32_16x16x32_bf16 v[58:61], v[54:57], v[42:45], 0
	s_nop 7
	ds_write_b32 v63, v58 offset:8448
	ds_write_b32 v62, v59 offset:8448
	ds_write_b32 v62, v60 offset:8976
	ds_write_b32 v62, v61 offset:9504
	v_mfma_f32_16x16x32_bf16 v[58:61], v[54:57], v[38:41], 0
	s_nop 7
	ds_write_b32 v63, v58 offset:8512
	ds_write_b32 v62, v59 offset:8512
	ds_write_b32 v62, v60 offset:9040
	ds_write_b32 v62, v61 offset:9568
	v_mfma_f32_16x16x32_bf16 v[58:61], v[54:57], v[50:53], 0
	s_nop 7
	ds_write_b32 v63, v58 offset:8576
	ds_write_b32 v62, v59 offset:8576
	ds_write_b32 v62, v60 offset:9104
	ds_write_b32 v62, v61 offset:9632
	v_mfma_f32_16x16x32_bf16 v[54:57], v[54:57], v[46:49], 0
	s_nop 7
	ds_write_b32 v63, v54 offset:8640
	ds_write_b32 v62, v55 offset:8640
	ds_write_b32 v62, v56 offset:9168
	ds_write_b32 v62, v57 offset:9696
	v_mov_b32_e32 v54, v82
	v_mov_b32_e32 v55, v81
	s_waitcnt lgkmcnt(0)
	s_barrier
; DI u16 f2bf(float x) { return (u16)(pk2(x, 0.f) & 0xffffu); }
; template <bool OUT>
; DI void s5_item(int wv0, PP p, int item, unsigned char* smem) {
;     ...
; #pragma unroll 4
;     for (int t = 0; t < 16; ++t) {
;       const float bur = sBU[t * 132 + lane], bui = sBU[t * 132 + 64 + lane];
;       const float nr = lbr * hr - lbi * hi + bur;
;       const float nim = lbr * hi + lbi * hr + bui;
;       hr = nr;
;       hi = nim;
;       if (OUT) {
;         sH[t * 136 + lane] = f2bf(hr);
;         sH[t * 136 + 64 + lane] = f2bf(hi);
;       }
;     }
.LBB0_788:
	v_add_u32_e32 v117, 32, v54
	v_add_u32_e32 v118, 1088, v54
	v_add_u32_e32 v119, 2144, v54
	v_add_u32_e32 v120, 3200, v54
	v_add_u32_e32 v121, 4256, v54
	v_add_u32_e32 v122, 5312, v54
	v_add_u32_e32 v123, 6368, v54
	v_add_u32_e32 v124, 7424, v54
	ds_read2st64_b32 v[152:153], v117 offset1:1
	ds_read2_b32 v[154:155], v117 offset0:132 offset1:196
	ds_read2st64_b32 v[156:157], v118 offset1:1
	ds_read2_b32 v[158:159], v118 offset0:132 offset1:196
	ds_read2st64_b32 v[160:161], v119 offset1:1
	ds_read2_b32 v[162:163], v119 offset0:132 offset1:196
	ds_read2st64_b32 v[164:165], v120 offset1:1
	ds_read2_b32 v[166:167], v120 offset0:132 offset1:196
	ds_read2st64_b32 v[168:169], v121 offset1:1
	ds_read2_b32 v[170:171], v121 offset0:132 offset1:196
	ds_read2st64_b32 v[172:173], v122 offset1:1
	ds_read2_b32 v[174:175], v122 offset0:132 offset1:196
	ds_read2st64_b32 v[176:177], v123 offset1:1
	ds_read2_b32 v[178:179], v123 offset0:132 offset1:196
	ds_read2st64_b32 v[180:181], v124 offset1:1
	ds_read2_b32 v[182:183], v124 offset0:132 offset1:196
	v_add_u32_e32 v126, 0x12820, v55
	s_waitcnt lgkmcnt(0)
	v_mul_f32_e32 v184, v70, v69
	v_mul_f32_e32 v185, v71, v69
	v_fma_f32 v186, v66, v68, -v184
	v_fma_f32 v187, v67, v68, v185
	v_add_f32_e32 v192, v186, v152
	v_add_f32_e32 v193, v187, v153
	v_cvt_pk_bf16_f32 v190, v192, s0
	ds_write_b16 v126, v190
	v_cvt_pk_bf16_f32 v191, v193, s0
	ds_write_b16 v126, v191 offset:128
	v_mul_f32_e32 v184, v70, v193
	v_mul_f32_e32 v185, v71, v193
	v_fma_f32 v186, v66, v192, -v184
	v_fma_f32 v187, v67, v192, v185
	v_add_f32_e32 v68, v186, v154
	v_add_f32_e32 v69, v187, v155
	v_cvt_pk_bf16_f32 v190, v68, s0
	ds_write_b16 v126, v190 offset:272
	v_cvt_pk_bf16_f32 v191, v69, s0
	ds_write_b16 v126, v191 offset:400
	v_mul_f32_e32 v184, v70, v69
	v_mul_f32_e32 v185, v71, v69
	v_fma_f32 v186, v66, v68, -v184
	v_fma_f32 v187, v67, v68, v185
	v_add_f32_e32 v192, v186, v156
	v_add_f32_e32 v193, v187, v157
	v_cvt_pk_bf16_f32 v190, v192, s0
	ds_write_b16 v126, v190 offset:544
	v_cvt_pk_bf16_f32 v191, v193, s0
	ds_write_b16 v126, v191 offset:672
	v_mul_f32_e32 v184, v70, v193
	v_mul_f32_e32 v185, v71, v193
	v_fma_f32 v186, v66, v192, -v184
	v_fma_f32 v187, v67, v192, v185
	v_add_f32_e32 v68, v186, v158
	v_add_f32_e32 v69, v187, v159
	v_cvt_pk_bf16_f32 v190, v68, s0
	ds_write_b16 v126, v190 offset:816
	v_cvt_pk_bf16_f32 v191, v69, s0
	ds_write_b16 v126, v191 offset:944
	v_mul_f32_e32 v184, v70, v69
	v_mul_f32_e32 v185, v71, v69
	v_fma_f32 v186, v66, v68, -v184
	v_fma_f32 v187, v67, v68, v185
	v_add_f32_e32 v192, v186, v160
	v_add_f32_e32 v193, v187, v161
	v_cvt_pk_bf16_f32 v190, v192, s0
	ds_write_b16 v126, v190 offset:1088
	v_cvt_pk_bf16_f32 v191, v193, s0
	ds_write_b16 v126, v191 offset:1216
	v_mul_f32_e32 v184, v70, v193
	v_mul_f32_e32 v185, v71, v193
	v_fma_f32 v186, v66, v192, -v184
	v_fma_f32 v187, v67, v192, v185
	v_add_f32_e32 v68, v186, v162
	v_add_f32_e32 v69, v187, v163
	v_cvt_pk_bf16_f32 v190, v68, s0
	ds_write_b16 v126, v190 offset:1360
	v_cvt_pk_bf16_f32 v191, v69, s0
	ds_write_b16 v126, v191 offset:1488
	v_mul_f32_e32 v184, v70, v69
	v_mul_f32_e32 v185, v71, v69
	v_fma_f32 v186, v66, v68, -v184
	v_fma_f32 v187, v67, v68, v185
	v_add_f32_e32 v192, v186, v164
	v_add_f32_e32 v193, v187, v165
	v_cvt_pk_bf16_f32 v190, v192, s0
	ds_write_b16 v126, v190 offset:1632
	v_cvt_pk_bf16_f32 v191, v193, s0
	ds_write_b16 v126, v191 offset:1760
	v_mul_f32_e32 v184, v70, v193
	v_mul_f32_e32 v185, v71, v193
	v_fma_f32 v186, v66, v192, -v184
	v_fma_f32 v187, v67, v192, v185
	v_add_f32_e32 v68, v186, v166
	v_add_f32_e32 v69, v187, v167
	v_cvt_pk_bf16_f32 v190, v68, s0
	ds_write_b16 v126, v190 offset:1904
	v_cvt_pk_bf16_f32 v191, v69, s0
	ds_write_b16 v126, v191 offset:2032
	v_mul_f32_e32 v184, v70, v69
	v_mul_f32_e32 v185, v71, v69
	v_fma_f32 v186, v66, v68, -v184
	v_fma_f32 v187, v67, v68, v185
	v_add_f32_e32 v192, v186, v168
	v_add_f32_e32 v193, v187, v169
	v_cvt_pk_bf16_f32 v190, v192, s0
	ds_write_b16 v126, v190 offset:2176
	v_cvt_pk_bf16_f32 v191, v193, s0
	ds_write_b16 v126, v191 offset:2304
	v_mul_f32_e32 v184, v70, v193
	v_mul_f32_e32 v185, v71, v193
	v_fma_f32 v186, v66, v192, -v184
	v_fma_f32 v187, v67, v192, v185
	v_add_f32_e32 v68, v186, v170
	v_add_f32_e32 v69, v187, v171
	v_cvt_pk_bf16_f32 v190, v68, s0
	ds_write_b16 v126, v190 offset:2448
	v_cvt_pk_bf16_f32 v191, v69, s0
	ds_write_b16 v126, v191 offset:2576
	v_mul_f32_e32 v184, v70, v69
	v_mul_f32_e32 v185, v71, v69
	v_fma_f32 v186, v66, v68, -v184
	v_fma_f32 v187, v67, v68, v185
	v_add_f32_e32 v192, v186, v172
	v_add_f32_e32 v193, v187, v173
	v_cvt_pk_bf16_f32 v190, v192, s0
	ds_write_b16 v126, v190 offset:2720
	v_cvt_pk_bf16_f32 v191, v193, s0
	ds_write_b16 v126, v191 offset:2848
	v_mul_f32_e32 v184, v70, v193
	v_mul_f32_e32 v185, v71, v193
	v_fma_f32 v186, v66, v192, -v184
	v_fma_f32 v187, v67, v192, v185
	v_add_f32_e32 v68, v186, v174
	v_add_f32_e32 v69, v187, v175
	v_cvt_pk_bf16_f32 v190, v68, s0
	ds_write_b16 v126, v190 offset:2992
	v_cvt_pk_bf16_f32 v191, v69, s0
	ds_write_b16 v126, v191 offset:3120
	v_mul_f32_e32 v184, v70, v69
	v_mul_f32_e32 v185, v71, v69
	v_fma_f32 v186, v66, v68, -v184
	v_fma_f32 v187, v67, v68, v185
	v_add_f32_e32 v192, v186, v176
	v_add_f32_e32 v193, v187, v177
	v_cvt_pk_bf16_f32 v190, v192, s0
	ds_write_b16 v126, v190 offset:3264
	v_cvt_pk_bf16_f32 v191, v193, s0
	ds_write_b16 v126, v191 offset:3392
	v_mul_f32_e32 v184, v70, v193
	v_mul_f32_e32 v185, v71, v193
	v_fma_f32 v186, v66, v192, -v184
	v_fma_f32 v187, v67, v192, v185
	v_add_f32_e32 v68, v186, v178
	v_add_f32_e32 v69, v187, v179
	v_cvt_pk_bf16_f32 v190, v68, s0
	ds_write_b16 v126, v190 offset:3536
	v_cvt_pk_bf16_f32 v191, v69, s0
	ds_write_b16 v126, v191 offset:3664
	v_mul_f32_e32 v184, v70, v69
	v_mul_f32_e32 v185, v71, v69
	v_fma_f32 v186, v66, v68, -v184
	v_fma_f32 v187, v67, v68, v185
	v_add_f32_e32 v192, v186, v180
	v_add_f32_e32 v193, v187, v181
	v_cvt_pk_bf16_f32 v190, v192, s0
	ds_write_b16 v126, v190 offset:3808
	v_cvt_pk_bf16_f32 v191, v193, s0
	ds_write_b16 v126, v191 offset:3936
	v_mul_f32_e32 v184, v70, v193
	v_mul_f32_e32 v185, v71, v193
	v_fma_f32 v186, v66, v192, -v184
	v_fma_f32 v187, v67, v192, v185
	v_add_f32_e32 v68, v186, v182
	v_add_f32_e32 v69, v187, v183
	v_cvt_pk_bf16_f32 v190, v68, s0
	ds_write_b16 v126, v190 offset:4080
	v_cvt_pk_bf16_f32 v191, v69, s0
	ds_write_b16 v126, v191 offset:4208
	s_waitcnt lgkmcnt(0)
	s_barrier
; DI u16 f2bf(float x) { return (u16)(pk2(x, 0.f) & 0xffffu); }
; DI float bf2f(u16 h) { return __uint_as_float(((unsigned)h) << 16); }
; DI f32x4 mfma16(bf16x8 a, bf16x8 b, f32x4 c) { return __builtin_amdgcn_mfma_f32_16x16x32_bf16(a, b, c, 0, 0, 0); }
; template <bool OUT>
; DI void s5_item(int wv0, PP p, int item, unsigned char* smem) {
;     ...
;   for (int sub = 0; sub < 4; ++sub) {
;     const bf16x8 ua = uall[sub];
; #pragma unroll
;     for (int nt = 0; nt < 8; ++nt) {
;       const f32x4 a = mfma16(ua, bb[nt], f32x4{0.f, 0.f, 0.f, 0.f});
; #pragma unroll
;       for (int j = 0; j < 4; ++j) sBU[(4 * fq + j) * 132 + 16 * nt + fr] = a[j];
;     }
;     __syncthreads();
;     ...
;     if (OUT) {
;       f32x4 y = {0.f, 0.f, 0.f, 0.f};
; #pragma unroll
;       for (int ks = 0; ks < 4; ++ks) y = mfma16(*(const bf16x8*)(sH + fr * 136 + 32 * ks + 8 * fq), cf[ks], y);
; #pragma unroll
;       for (int j = 0; j < 4; ++j) {
;         const size_t o = (size_t)(sub * 16 + 4 * fq + j) * 512 + fr;
;         YS[o] = f2bf(gelu_t(y[j] + dk * bf2f(usk[sub][j])));
;       }
;       __syncthreads();
	ds_read_b128 v[54:57], v0
	ds_read_b128 v[58:61], v0 offset:64
	s_waitcnt vmcnt(12)
	v_mfma_f32_16x16x32_bf16 v[26:29], v[18:21], v[26:29], 0
	s_waitcnt lgkmcnt(1)
	v_mfma_f32_16x16x32_bf16 v[54:57], v[54:57], v[14:17], 0
	s_waitcnt lgkmcnt(0)
	v_mfma_f32_16x16x32_bf16 v[54:57], v[58:61], v[10:13], v[54:57]
	ds_read_b128 v[58:61], v0 offset:128
	v_mfma_f32_16x16x32_bf16 v[22:25], v[18:21], v[22:25], 0
	s_waitcnt lgkmcnt(0)
	v_mfma_f32_16x16x32_bf16 v[54:57], v[58:61], v[6:9], v[54:57]
	ds_read_b128 v[58:61], v0 offset:192
	s_waitcnt lgkmcnt(0)
	v_mfma_f32_16x16x32_bf16 v[54:57], v[58:61], v[2:5], v[54:57]
	v_lshlrev_b32_e32 v58, 16, v90
	s_nop 6
	v_fma_f32 v54, v72, v58, v54
	v_mul_f32_e32 v58, 0x3d372713, v54
	v_mul_f32_e32 v58, v54, v58
	v_fma_f32 v58, v54, v58, v54
	v_mul_f32_e32 v58, 0x3f4c422a, v58
	v_add_f32_e32 v58, v58, v58
	v_mul_f32_e32 v58, 0x3fb8aa3b, v58
	v_exp_f32_e32 v58, v58
	v_mul_f32_e32 v54, 0.5, v54
	v_add_f32_e32 v58, 1.0, v58
	v_div_scale_f32 v59, s[4:5], v58, v58, 2.0
	v_rcp_f32_e32 v60, v59
	s_nop 0
	v_fma_f32 v61, -v59, v60, 1.0
	v_fmac_f32_e32 v60, v61, v60
	v_div_scale_f32 v61, vcc, 2.0, v58, 2.0
	v_mul_f32_e32 v64, v61, v60
	v_fma_f32 v65, -v59, v64, v61
	v_fmac_f32_e32 v64, v65, v60
	v_fma_f32 v59, -v59, v64, v61
	v_div_fmas_f32 v59, v59, v60, v64
	v_div_fixup_f32 v58, v59, v58, 2.0
	v_sub_f32_e32 v58, 1.0, v58
	v_add_f32_e32 v58, 1.0, v58
	v_mul_f32_e32 v54, v54, v58
	v_cvt_pk_bf16_f32 v54, v54, s0
	global_store_short v89, v54, s[2:3]
	v_lshlrev_b32_e32 v54, 16, v88
	v_fma_f32 v54, v72, v54, v55
	v_mul_f32_e32 v55, 0x3d372713, v54
	v_mul_f32_e32 v55, v54, v55
	v_fma_f32 v55, v54, v55, v54
	v_mul_f32_e32 v55, 0x3f4c422a, v55
	v_add_f32_e32 v55, v55, v55
	v_mul_f32_e32 v55, 0x3fb8aa3b, v55
	v_exp_f32_e32 v55, v55
	v_mul_f32_e32 v54, 0.5, v54
	v_add_f32_e32 v55, 1.0, v55
	v_div_scale_f32 v58, s[4:5], v55, v55, 2.0
	v_rcp_f32_e32 v59, v58
	s_nop 0
	v_fma_f32 v60, -v58, v59, 1.0
	v_fmac_f32_e32 v59, v60, v59
	v_div_scale_f32 v60, vcc, 2.0, v55, 2.0
	v_mul_f32_e32 v61, v60, v59
	v_fma_f32 v64, -v58, v61, v60
	v_fmac_f32_e32 v61, v64, v59
	v_fma_f32 v58, -v58, v61, v60
	v_div_fmas_f32 v58, v58, v59, v61
	v_div_fixup_f32 v55, v58, v55, 2.0
	v_sub_f32_e32 v55, 1.0, v55
	v_add_f32_e32 v55, 1.0, v55
	v_mul_f32_e32 v54, v54, v55
	v_cvt_pk_bf16_f32 v54, v54, s0
	global_store_short v87, v54, s[2:3]
	v_lshlrev_b32_e32 v54, 16, v86
	v_fma_f32 v54, v72, v54, v56
	v_mul_f32_e32 v55, 0x3d372713, v54
	v_mul_f32_e32 v55, v54, v55
	v_fma_f32 v55, v54, v55, v54
	v_mul_f32_e32 v55, 0x3f4c422a, v55
	v_add_f32_e32 v55, v55, v55
	v_mul_f32_e32 v55, 0x3fb8aa3b, v55
	v_exp_f32_e32 v55, v55
	v_mul_f32_e32 v54, 0.5, v54
	v_add_f32_e32 v55, 1.0, v55
	v_div_scale_f32 v56, s[4:5], v55, v55, 2.0
	v_rcp_f32_e32 v58, v56
	s_nop 0
	v_fma_f32 v59, -v56, v58, 1.0
	v_fmac_f32_e32 v58, v59, v58
	v_div_scale_f32 v59, vcc, 2.0, v55, 2.0
	v_mul_f32_e32 v60, v59, v58
	v_fma_f32 v61, -v56, v60, v59
	v_fmac_f32_e32 v60, v61, v58
	v_fma_f32 v56, -v56, v60, v59
	v_div_fmas_f32 v56, v56, v58, v60
	v_div_fixup_f32 v55, v56, v55, 2.0
	v_sub_f32_e32 v55, 1.0, v55
	v_add_f32_e32 v55, 1.0, v55
	v_mul_f32_e32 v54, v54, v55
	v_cvt_pk_bf16_f32 v54, v54, s0
	global_store_short v85, v54, s[2:3]
	v_lshlrev_b32_e32 v54, 16, v84
	v_fmac_f32_e32 v57, v72, v54
	v_mul_f32_e32 v54, 0x3d372713, v57
	v_mul_f32_e32 v54, v57, v54
	v_fma_f32 v54, v57, v54, v57
	v_mul_f32_e32 v54, 0x3f4c422a, v54
	v_add_f32_e32 v54, v54, v54
	v_mul_f32_e32 v54, 0x3fb8aa3b, v54
	v_exp_f32_e32 v54, v54
	s_nop 0
	v_add_f32_e32 v54, 1.0, v54
	v_div_scale_f32 v55, s[4:5], v54, v54, 2.0
	v_rcp_f32_e32 v56, v55
	s_mov_b32 s4, 16
	v_fma_f32 v58, -v55, v56, 1.0
	v_fmac_f32_e32 v56, v58, v56
	v_div_scale_f32 v58, vcc, 2.0, v54, 2.0
	v_mul_f32_e32 v59, v58, v56
	v_fma_f32 v60, -v55, v59, v58
	v_fmac_f32_e32 v59, v60, v56
	v_fma_f32 v55, -v55, v59, v58
	v_div_fmas_f32 v55, v55, v56, v59
	v_div_fixup_f32 v54, v55, v54, 2.0
	v_sub_f32_e32 v54, 1.0, v54
	v_mul_f32_e32 v55, 0.5, v57
	v_add_f32_e32 v54, 1.0, v54
	v_mul_f32_e32 v54, v55, v54
	v_cvt_pk_bf16_f32 v54, v54, s0
	global_store_short v83, v54, s[2:3]
	s_barrier
	ds_write_b32 v63, v26 offset:8192
	ds_write_b32 v62, v27 offset:8192
	ds_write_b32 v62, v28 offset:8720
	ds_write_b32 v62, v29 offset:9248
	ds_write_b32 v63, v22 offset:8256
	ds_write_b32 v62, v23 offset:8256
	ds_write_b32 v62, v24 offset:8784
	ds_write_b32 v62, v25 offset:9312
	v_mfma_f32_16x16x32_bf16 v[22:25], v[18:21], v[34:37], 0
	s_nop 7
	ds_write_b32 v63, v22 offset:8320
	ds_write_b32 v62, v23 offset:8320
	ds_write_b32 v62, v24 offset:8848
	ds_write_b32 v62, v25 offset:9376
	v_mfma_f32_16x16x32_bf16 v[22:25], v[18:21], v[30:33], 0
	s_nop 7
	ds_write_b32 v63, v22 offset:8384
	ds_write_b32 v62, v23 offset:8384
	ds_write_b32 v62, v24 offset:8912
	ds_write_b32 v62, v25 offset:9440
	v_mfma_f32_16x16x32_bf16 v[22:25], v[18:21], v[42:45], 0
	s_nop 7
	ds_write_b32 v63, v22 offset:8448
	ds_write_b32 v62, v23 offset:8448
	ds_write_b32 v62, v24 offset:8976
	ds_write_b32 v62, v25 offset:9504
	v_mfma_f32_16x16x32_bf16 v[22:25], v[18:21], v[38:41], 0
	s_nop 7
	ds_write_b32 v63, v22 offset:8512
	ds_write_b32 v62, v23 offset:8512
	ds_write_b32 v62, v24 offset:9040
	ds_write_b32 v62, v25 offset:9568
	v_mfma_f32_16x16x32_bf16 v[22:25], v[18:21], v[50:53], 0
	s_nop 7
	ds_write_b32 v63, v22 offset:8576
	ds_write_b32 v62, v23 offset:8576
	ds_write_b32 v62, v24 offset:9104
	ds_write_b32 v62, v25 offset:9632
	v_mfma_f32_16x16x32_bf16 v[18:21], v[18:21], v[46:49], 0
	s_nop 7
	ds_write_b32 v63, v18 offset:8640
	ds_write_b32 v62, v19 offset:8640
	ds_write_b32 v62, v20 offset:9168
	ds_write_b32 v62, v21 offset:9696
	s_waitcnt lgkmcnt(0)
	s_barrier
; DI u16 f2bf(float x) { return (u16)(pk2(x, 0.f) & 0xffffu); }
; template <bool OUT>
; DI void s5_item(int wv0, PP p, int item, unsigned char* smem) {
;     ...
; #pragma unroll 4
;     for (int t = 0; t < 16; ++t) {
;       const float bur = sBU[t * 132 + lane], bui = sBU[t * 132 + 64 + lane];
;       const float nr = lbr * hr - lbi * hi + bur;
;       const float nim = lbr * hi + lbi * hr + bui;
;       hr = nr;
;       hi = nim;
;       if (OUT) {
;         sH[t * 136 + lane] = f2bf(hr);
;         sH[t * 136 + 64 + lane] = f2bf(hi);
;       }
;     }
.LBB0_790:
	v_add_u32_e32 v117, 32, v82
	v_add_u32_e32 v118, 1088, v82
	v_add_u32_e32 v119, 2144, v82
	v_add_u32_e32 v120, 3200, v82
	v_add_u32_e32 v121, 4256, v82
	v_add_u32_e32 v122, 5312, v82
	v_add_u32_e32 v123, 6368, v82
	v_add_u32_e32 v124, 7424, v82
	ds_read2st64_b32 v[152:153], v117 offset1:1
	ds_read2_b32 v[154:155], v117 offset0:132 offset1:196
	ds_read2st64_b32 v[156:157], v118 offset1:1
	ds_read2_b32 v[158:159], v118 offset0:132 offset1:196
	ds_read2st64_b32 v[160:161], v119 offset1:1
	ds_read2_b32 v[162:163], v119 offset0:132 offset1:196
	ds_read2st64_b32 v[164:165], v120 offset1:1
	ds_read2_b32 v[166:167], v120 offset0:132 offset1:196
	ds_read2st64_b32 v[168:169], v121 offset1:1
	ds_read2_b32 v[170:171], v121 offset0:132 offset1:196
	ds_read2st64_b32 v[172:173], v122 offset1:1
	ds_read2_b32 v[174:175], v122 offset0:132 offset1:196
	ds_read2st64_b32 v[176:177], v123 offset1:1
	ds_read2_b32 v[178:179], v123 offset0:132 offset1:196
	ds_read2st64_b32 v[180:181], v124 offset1:1
	ds_read2_b32 v[182:183], v124 offset0:132 offset1:196
	v_add_u32_e32 v126, 0x12820, v81
	s_waitcnt lgkmcnt(0)
	v_mul_f32_e32 v184, v70, v69
	v_mul_f32_e32 v185, v71, v69
	v_fma_f32 v186, v66, v68, -v184
	v_fma_f32 v187, v67, v68, v185
	v_add_f32_e32 v192, v186, v152
	v_add_f32_e32 v193, v187, v153
	v_cvt_pk_bf16_f32 v190, v192, s0
	ds_write_b16 v126, v190
	v_cvt_pk_bf16_f32 v191, v193, s0
	ds_write_b16 v126, v191 offset:128
	v_mul_f32_e32 v184, v70, v193
	v_mul_f32_e32 v185, v71, v193
	v_fma_f32 v186, v66, v192, -v184
	v_fma_f32 v187, v67, v192, v185
	v_add_f32_e32 v68, v186, v154
	v_add_f32_e32 v69, v187, v155
	v_cvt_pk_bf16_f32 v190, v68, s0
	ds_write_b16 v126, v190 offset:272
	v_cvt_pk_bf16_f32 v191, v69, s0
	ds_write_b16 v126, v191 offset:400
	v_mul_f32_e32 v184, v70, v69
	v_mul_f32_e32 v185, v71, v69
	v_fma_f32 v186, v66, v68, -v184
	v_fma_f32 v187, v67, v68, v185
	v_add_f32_e32 v192, v186, v156
	v_add_f32_e32 v193, v187, v157
	v_cvt_pk_bf16_f32 v190, v192, s0
	ds_write_b16 v126, v190 offset:544
	v_cvt_pk_bf16_f32 v191, v193, s0
	ds_write_b16 v126, v191 offset:672
	v_mul_f32_e32 v184, v70, v193
	v_mul_f32_e32 v185, v71, v193
	v_fma_f32 v186, v66, v192, -v184
	v_fma_f32 v187, v67, v192, v185
	v_add_f32_e32 v68, v186, v158
	v_add_f32_e32 v69, v187, v159
	v_cvt_pk_bf16_f32 v190, v68, s0
	ds_write_b16 v126, v190 offset:816
	v_cvt_pk_bf16_f32 v191, v69, s0
	ds_write_b16 v126, v191 offset:944
	v_mul_f32_e32 v184, v70, v69
	v_mul_f32_e32 v185, v71, v69
	v_fma_f32 v186, v66, v68, -v184
	v_fma_f32 v187, v67, v68, v185
	v_add_f32_e32 v192, v186, v160
	v_add_f32_e32 v193, v187, v161
	v_cvt_pk_bf16_f32 v190, v192, s0
	ds_write_b16 v126, v190 offset:1088
	v_cvt_pk_bf16_f32 v191, v193, s0
	ds_write_b16 v126, v191 offset:1216
	v_mul_f32_e32 v184, v70, v193
	v_mul_f32_e32 v185, v71, v193
	v_fma_f32 v186, v66, v192, -v184
	v_fma_f32 v187, v67, v192, v185
	v_add_f32_e32 v68, v186, v162
	v_add_f32_e32 v69, v187, v163
	v_cvt_pk_bf16_f32 v190, v68, s0
	ds_write_b16 v126, v190 offset:1360
	v_cvt_pk_bf16_f32 v191, v69, s0
	ds_write_b16 v126, v191 offset:1488
	v_mul_f32_e32 v184, v70, v69
	v_mul_f32_e32 v185, v71, v69
	v_fma_f32 v186, v66, v68, -v184
	v_fma_f32 v187, v67, v68, v185
	v_add_f32_e32 v192, v186, v164
	v_add_f32_e32 v193, v187, v165
	v_cvt_pk_bf16_f32 v190, v192, s0
	ds_write_b16 v126, v190 offset:1632
	v_cvt_pk_bf16_f32 v191, v193, s0
	ds_write_b16 v126, v191 offset:1760
	v_mul_f32_e32 v184, v70, v193
	v_mul_f32_e32 v185, v71, v193
	v_fma_f32 v186, v66, v192, -v184
	v_fma_f32 v187, v67, v192, v185
	v_add_f32_e32 v68, v186, v166
	v_add_f32_e32 v69, v187, v167
	v_cvt_pk_bf16_f32 v190, v68, s0
	ds_write_b16 v126, v190 offset:1904
	v_cvt_pk_bf16_f32 v191, v69, s0
	ds_write_b16 v126, v191 offset:2032
	v_mul_f32_e32 v184, v70, v69
	v_mul_f32_e32 v185, v71, v69
	v_fma_f32 v186, v66, v68, -v184
	v_fma_f32 v187, v67, v68, v185
	v_add_f32_e32 v192, v186, v168
	v_add_f32_e32 v193, v187, v169
	v_cvt_pk_bf16_f32 v190, v192, s0
	ds_write_b16 v126, v190 offset:2176
	v_cvt_pk_bf16_f32 v191, v193, s0
	ds_write_b16 v126, v191 offset:2304
	v_mul_f32_e32 v184, v70, v193
	v_mul_f32_e32 v185, v71, v193
	v_fma_f32 v186, v66, v192, -v184
	v_fma_f32 v187, v67, v192, v185
	v_add_f32_e32 v68, v186, v170
	v_add_f32_e32 v69, v187, v171
	v_cvt_pk_bf16_f32 v190, v68, s0
	ds_write_b16 v126, v190 offset:2448
	v_cvt_pk_bf16_f32 v191, v69, s0
	ds_write_b16 v126, v191 offset:2576
	v_mul_f32_e32 v184, v70, v69
	v_mul_f32_e32 v185, v71, v69
	v_fma_f32 v186, v66, v68, -v184
	v_fma_f32 v187, v67, v68, v185
	v_add_f32_e32 v192, v186, v172
	v_add_f32_e32 v193, v187, v173
	v_cvt_pk_bf16_f32 v190, v192, s0
	ds_write_b16 v126, v190 offset:2720
	v_cvt_pk_bf16_f32 v191, v193, s0
	ds_write_b16 v126, v191 offset:2848
	v_mul_f32_e32 v184, v70, v193
	v_mul_f32_e32 v185, v71, v193
	v_fma_f32 v186, v66, v192, -v184
	v_fma_f32 v187, v67, v192, v185
	v_add_f32_e32 v68, v186, v174
	v_add_f32_e32 v69, v187, v175
	v_cvt_pk_bf16_f32 v190, v68, s0
	ds_write_b16 v126, v190 offset:2992
	v_cvt_pk_bf16_f32 v191, v69, s0
	ds_write_b16 v126, v191 offset:3120
	v_mul_f32_e32 v184, v70, v69
	v_mul_f32_e32 v185, v71, v69
	v_fma_f32 v186, v66, v68, -v184
	v_fma_f32 v187, v67, v68, v185
	v_add_f32_e32 v192, v186, v176
	v_add_f32_e32 v193, v187, v177
	v_cvt_pk_bf16_f32 v190, v192, s0
	ds_write_b16 v126, v190 offset:3264
	v_cvt_pk_bf16_f32 v191, v193, s0
	ds_write_b16 v126, v191 offset:3392
	v_mul_f32_e32 v184, v70, v193
	v_mul_f32_e32 v185, v71, v193
	v_fma_f32 v186, v66, v192, -v184
	v_fma_f32 v187, v67, v192, v185
	v_add_f32_e32 v68, v186, v178
	v_add_f32_e32 v69, v187, v179
	v_cvt_pk_bf16_f32 v190, v68, s0
	ds_write_b16 v126, v190 offset:3536
	v_cvt_pk_bf16_f32 v191, v69, s0
	ds_write_b16 v126, v191 offset:3664
	v_mul_f32_e32 v184, v70, v69
	v_mul_f32_e32 v185, v71, v69
	v_fma_f32 v186, v66, v68, -v184
	v_fma_f32 v187, v67, v68, v185
	v_add_f32_e32 v192, v186, v180
	v_add_f32_e32 v193, v187, v181
	v_cvt_pk_bf16_f32 v190, v192, s0
	ds_write_b16 v126, v190 offset:3808
	v_cvt_pk_bf16_f32 v191, v193, s0
	ds_write_b16 v126, v191 offset:3936
	v_mul_f32_e32 v184, v70, v193
	v_mul_f32_e32 v185, v71, v193
	v_fma_f32 v186, v66, v192, -v184
	v_fma_f32 v187, v67, v192, v185
	v_add_f32_e32 v68, v186, v182
	v_add_f32_e32 v69, v187, v183
	v_cvt_pk_bf16_f32 v190, v68, s0
	ds_write_b16 v126, v190 offset:4080
	v_cvt_pk_bf16_f32 v191, v69, s0
	ds_write_b16 v126, v191 offset:4208
	s_waitcnt lgkmcnt(0)
	s_barrier
; DI u16 f2bf(float x) { return (u16)(pk2(x, 0.f) & 0xffffu); }
; DI float bf2f(u16 h) { return __uint_as_float(((unsigned)h) << 16); }
; DI f32x4 mfma16(bf16x8 a, bf16x8 b, f32x4 c) { return __builtin_amdgcn_mfma_f32_16x16x32_bf16(a, b, c, 0, 0, 0); }
; template <bool OUT>
; DI void s5_item(int wv0, PP p, int item, unsigned char* smem) {
;     ...
;     if (OUT) {
;       f32x4 y = {0.f, 0.f, 0.f, 0.f};
; #pragma unroll
;       for (int ks = 0; ks < 4; ++ks) y = mfma16(*(const bf16x8*)(sH + fr * 136 + 32 * ks + 8 * fq), cf[ks], y);
; #pragma unroll
;       for (int j = 0; j < 4; ++j) {
;         const size_t o = (size_t)(sub * 16 + 4 * fq + j) * 512 + fr;
;         YS[o] = f2bf(gelu_t(y[j] + dk * bf2f(usk[sub][j])));
;       }
;       __syncthreads();
;     }
;   }
;   if (!OUT) *HL = make_float2(hr, hi);
;   __syncthreads();
	ds_read_b128 v[18:21], v0
	s_waitcnt lgkmcnt(0)
	v_mfma_f32_16x16x32_bf16 v[14:17], v[18:21], v[14:17], 0
	ds_read_b128 v[18:21], v0 offset:64
	s_waitcnt lgkmcnt(0)
	v_mfma_f32_16x16x32_bf16 v[10:13], v[18:21], v[10:13], v[14:17]
	s_nop 4
	ds_read_b128 v[14:17], v0 offset:128
	s_waitcnt lgkmcnt(0)
	v_mfma_f32_16x16x32_bf16 v[6:9], v[14:17], v[6:9], v[10:13]
	s_nop 2
	ds_read_b128 v[10:13], v0 offset:192
	s_waitcnt vmcnt(15)
	v_lshlrev_b32_e32 v0, 16, v80
	s_waitcnt lgkmcnt(0)
	v_mfma_f32_16x16x32_bf16 v[2:5], v[10:13], v[2:5], v[6:9]
	s_nop 7
	v_fma_f32 v0, v72, v0, v2
	v_mul_f32_e32 v2, 0x3d372713, v0
	v_mul_f32_e32 v2, v0, v2
	v_fma_f32 v2, v0, v2, v0
	v_mul_f32_e32 v2, 0x3f4c422a, v2
	v_add_f32_e32 v2, v2, v2
	v_mul_f32_e32 v2, 0x3fb8aa3b, v2
	v_exp_f32_e32 v2, v2
	v_mul_f32_e32 v0, 0.5, v0
	v_add_f32_e32 v2, 1.0, v2
	v_div_scale_f32 v6, s[4:5], v2, v2, 2.0
	v_rcp_f32_e32 v7, v6
	s_nop 0
	v_fma_f32 v8, -v6, v7, 1.0
	v_fmac_f32_e32 v7, v8, v7
	v_div_scale_f32 v8, vcc, 2.0, v2, 2.0
	v_mul_f32_e32 v9, v8, v7
	v_fma_f32 v10, -v6, v9, v8
	v_fmac_f32_e32 v9, v10, v7
	v_fma_f32 v6, -v6, v9, v8
	v_div_fmas_f32 v6, v6, v7, v9
	v_div_fixup_f32 v2, v6, v2, 2.0
	v_sub_f32_e32 v2, 1.0, v2
	v_add_f32_e32 v2, 1.0, v2
	v_mul_f32_e32 v0, v0, v2
	v_cvt_pk_bf16_f32 v0, v0, s0
	global_store_short v79, v0, s[2:3]
	s_waitcnt vmcnt(15)
	v_lshlrev_b32_e32 v0, 16, v78
	v_fma_f32 v0, v72, v0, v3
	v_mul_f32_e32 v2, 0x3d372713, v0
	v_mul_f32_e32 v2, v0, v2
	v_fma_f32 v2, v0, v2, v0
	v_mul_f32_e32 v2, 0x3f4c422a, v2
	v_add_f32_e32 v2, v2, v2
	v_mul_f32_e32 v2, 0x3fb8aa3b, v2
	v_exp_f32_e32 v2, v2
	v_mul_f32_e32 v0, 0.5, v0
	v_add_f32_e32 v2, 1.0, v2
	v_div_scale_f32 v3, s[4:5], v2, v2, 2.0
	v_rcp_f32_e32 v6, v3
	s_nop 0
	v_fma_f32 v7, -v3, v6, 1.0
	v_fmac_f32_e32 v6, v7, v6
	v_div_scale_f32 v7, vcc, 2.0, v2, 2.0
	v_mul_f32_e32 v8, v7, v6
	v_fma_f32 v9, -v3, v8, v7
	v_fmac_f32_e32 v8, v9, v6
	v_fma_f32 v3, -v3, v8, v7
	v_div_fmas_f32 v3, v3, v6, v8
	v_div_fixup_f32 v2, v3, v2, 2.0
	v_sub_f32_e32 v2, 1.0, v2
	v_add_f32_e32 v2, 1.0, v2
	v_mul_f32_e32 v0, v0, v2
	v_cvt_pk_bf16_f32 v0, v0, s0
	global_store_short v77, v0, s[2:3]
	s_waitcnt vmcnt(15)
	v_lshlrev_b32_e32 v0, 16, v76
	v_fma_f32 v0, v72, v0, v4
	v_mul_f32_e32 v2, 0x3d372713, v0
	v_mul_f32_e32 v2, v0, v2
	v_fma_f32 v2, v0, v2, v0
	v_mul_f32_e32 v2, 0x3f4c422a, v2
	v_add_f32_e32 v2, v2, v2
	v_mul_f32_e32 v2, 0x3fb8aa3b, v2
	v_exp_f32_e32 v2, v2
	v_mul_f32_e32 v0, 0.5, v0
	v_add_f32_e32 v2, 1.0, v2
	v_div_scale_f32 v3, s[4:5], v2, v2, 2.0
	v_rcp_f32_e32 v4, v3
	s_nop 0
	v_fma_f32 v6, -v3, v4, 1.0
	v_fmac_f32_e32 v4, v6, v4
	v_div_scale_f32 v6, vcc, 2.0, v2, 2.0
	v_mul_f32_e32 v7, v6, v4
	v_fma_f32 v8, -v3, v7, v6
	v_fmac_f32_e32 v7, v8, v4
	v_fma_f32 v3, -v3, v7, v6
	v_div_fmas_f32 v3, v3, v4, v7
	v_div_fixup_f32 v2, v3, v2, 2.0
	v_sub_f32_e32 v2, 1.0, v2
	v_add_f32_e32 v2, 1.0, v2
	v_mul_f32_e32 v0, v0, v2
	v_cvt_pk_bf16_f32 v0, v0, s0
	global_store_short v75, v0, s[2:3]
	s_waitcnt vmcnt(15)
	v_lshlrev_b32_e32 v0, 16, v74
	v_fmac_f32_e32 v5, v72, v0
	v_mul_f32_e32 v0, 0x3d372713, v5
	v_mul_f32_e32 v0, v5, v0
	v_fma_f32 v0, v5, v0, v5
	v_mul_f32_e32 v0, 0x3f4c422a, v0
	v_add_f32_e32 v0, v0, v0
	v_mul_f32_e32 v0, 0x3fb8aa3b, v0
	v_exp_f32_e32 v0, v0
	s_nop 0
	v_add_f32_e32 v0, 1.0, v0
	v_div_scale_f32 v2, s[4:5], v0, v0, 2.0
	v_rcp_f32_e32 v3, v2
	s_nop 0
	v_fma_f32 v4, -v2, v3, 1.0
	v_fmac_f32_e32 v3, v4, v3
	v_div_scale_f32 v4, vcc, 2.0, v0, 2.0
	v_mul_f32_e32 v6, v4, v3
	v_fma_f32 v7, -v2, v6, v4
	v_fmac_f32_e32 v6, v7, v3
	v_fma_f32 v2, -v2, v6, v4
	v_div_fmas_f32 v2, v2, v3, v6
	v_div_fixup_f32 v0, v2, v0, 2.0
	v_sub_f32_e32 v0, 1.0, v0
	v_mul_f32_e32 v2, 0.5, v5
	v_add_f32_e32 v0, 1.0, v0
	v_mul_f32_e32 v0, v2, v0
	v_cvt_pk_bf16_f32 v0, v0, s0
	global_store_short v73, v0, s[2:3]
	s_barrier
	s_barrier
	s_mov_b64 s[2:3], 0
